# cache policy: FFN hidden (HID) epilogue stores sc1 nt (write-through without L2 allocation)
# speedup vs baseline: 1.0138x; 1.0096x over previous
.LBB0_495:
	s_waitcnt lgkmcnt(0)
	v_mul_f32_e32 v146, 0xbfb8aa3b, v144
	v_pk_mul_f32 v[148:149], v[126:127], v[146:147] op_sel_hi:[1,0]
	v_mul_f32_e32 v144, v144, v144
	v_exp_f32_e32 v148, v148
	v_exp_f32_e32 v149, v149
	v_pk_mul_f32 v[122:123], v[126:127], v[122:123]
	v_pk_mul_f32 v[124:125], v[128:129], v[124:125]
	v_pk_mul_f32 v[120:121], v[116:117], v[120:121]
	v_pk_add_f32 v[148:149], v[148:149], 1.0 op_sel_hi:[1,0]
	v_lshl_or_b32 v134, s90, 7, v141
	v_rcp_f32_e32 v148, v148
	v_rcp_f32_e32 v149, v149
	v_ashrrev_i32_e32 v135, 31, v134
	s_mov_b64 s[68:69], -1
	s_and_b64 vcc, exec, s[52:53]
	v_pk_mul_f32 v[126:127], v[144:145], v[148:149] op_sel_hi:[0,1]
	v_pk_mul_f32 v[122:123], v[122:123], v[126:127]
	v_pk_mul_f32 v[126:127], v[128:129], v[146:147] op_sel_hi:[1,0]
	s_nop 0
	v_exp_f32_e32 v126, v126
	v_exp_f32_e32 v127, v127
	s_nop 0
	v_pk_add_f32 v[126:127], v[126:127], 1.0 op_sel_hi:[1,0]
	s_nop 0
	v_rcp_f32_e32 v126, v126
	v_rcp_f32_e32 v127, v127
	s_nop 0
	v_pk_mul_f32 v[126:127], v[144:145], v[126:127] op_sel_hi:[0,1]
	v_pk_mul_f32 v[124:125], v[124:125], v[126:127]
	v_pk_mul_f32 v[126:127], v[114:115], v[146:147] op_sel_hi:[1,0]
	v_pk_mul_f32 v[114:115], v[114:115], v[118:119]
	v_exp_f32_e32 v126, v126
	v_exp_f32_e32 v127, v127
	s_nop 0
	v_pk_add_f32 v[126:127], v[126:127], 1.0 op_sel_hi:[1,0]
	s_nop 0
	v_rcp_f32_e32 v126, v126
	v_rcp_f32_e32 v127, v127
	s_nop 0
	v_pk_mul_f32 v[118:119], v[144:145], v[126:127] op_sel_hi:[0,1]
	v_pk_mul_f32 v[118:119], v[114:115], v[118:119]
	v_pk_mul_f32 v[114:115], v[116:117], v[146:147] op_sel_hi:[1,0]
	s_nop 0
	v_exp_f32_e32 v114, v114
	v_exp_f32_e32 v115, v115
	s_nop 0
	v_pk_add_f32 v[114:115], v[114:115], 1.0 op_sel_hi:[1,0]
	s_nop 0
	v_rcp_f32_e32 v114, v114
	v_rcp_f32_e32 v115, v115
	s_nop 0
	v_pk_mul_f32 v[114:115], v[144:145], v[114:115] op_sel_hi:[0,1]
	v_pk_mul_f32 v[120:121], v[120:121], v[114:115]
	v_cvt_pk_bf16_f32 v114, v122, v123
	v_cvt_pk_bf16_f32 v115, v124, v125
	v_cvt_pk_bf16_f32 v116, v118, v119
	v_mov_b64_e32 v[118:119], s[40:41]
	v_mad_u64_u32 v[118:119], s[20:21], v136, s17, v[118:119]
	v_cvt_pk_bf16_f32 v117, v120, v121
	v_mov_b32_e32 v120, v119
	v_mad_u64_u32 v[120:121], s[20:21], v137, s17, v[120:121]
	v_mov_b32_e32 v119, v120
	v_lshl_add_u64 v[150:151], v[134:135], 1, v[118:119]
	global_store_dwordx4 v[150:151], v[114:117], off sc1 nt
	s_nop 1
	s_cbranch_vccnz .LBB0_497
	ds_read_b32 v116, v143 offset:64
	s_mov_b64 s[68:69], 0

.LBB0_499:
	s_waitcnt lgkmcnt(0)
	v_mul_f32_e32 v118, 0xbfb8aa3b, v116
	v_pk_mul_f32 v[120:121], v[110:111], v[118:119] op_sel_hi:[1,0]
	v_mul_f32_e32 v116, v116, v116
	v_exp_f32_e32 v120, v120
	v_exp_f32_e32 v121, v121
	v_pk_mul_f32 v[106:107], v[110:111], v[106:107]
	v_pk_mul_f32 v[108:109], v[112:113], v[108:109]
	v_pk_mul_f32 v[104:105], v[100:101], v[104:105]
	v_pk_add_f32 v[120:121], v[120:121], 1.0 op_sel_hi:[1,0]
	s_mov_b64 s[68:69], -1
	v_rcp_f32_e32 v120, v120
	v_rcp_f32_e32 v121, v121
	s_and_b64 vcc, exec, s[52:53]
	v_pk_mul_f32 v[110:111], v[116:117], v[120:121] op_sel_hi:[0,1]
	v_pk_mul_f32 v[106:107], v[106:107], v[110:111]
	v_pk_mul_f32 v[110:111], v[112:113], v[118:119] op_sel_hi:[1,0]
	s_nop 0
	v_exp_f32_e32 v110, v110
	v_exp_f32_e32 v111, v111
	s_nop 0
	v_pk_add_f32 v[110:111], v[110:111], 1.0 op_sel_hi:[1,0]
	s_nop 0
	v_rcp_f32_e32 v110, v110
	v_rcp_f32_e32 v111, v111
	s_nop 0
	v_pk_mul_f32 v[110:111], v[116:117], v[110:111] op_sel_hi:[0,1]
	v_pk_mul_f32 v[108:109], v[108:109], v[110:111]
	v_pk_mul_f32 v[110:111], v[98:99], v[118:119] op_sel_hi:[1,0]
	v_pk_mul_f32 v[98:99], v[98:99], v[102:103]
	v_exp_f32_e32 v110, v110
	v_exp_f32_e32 v111, v111
	s_nop 0
	v_pk_add_f32 v[110:111], v[110:111], 1.0 op_sel_hi:[1,0]
	s_nop 0
	v_rcp_f32_e32 v110, v110
	v_rcp_f32_e32 v111, v111
	s_nop 0
	v_pk_mul_f32 v[102:103], v[116:117], v[110:111] op_sel_hi:[0,1]
	v_pk_mul_f32 v[102:103], v[98:99], v[102:103]
	v_pk_mul_f32 v[98:99], v[100:101], v[118:119] op_sel_hi:[1,0]
	s_nop 0
	v_exp_f32_e32 v98, v98
	v_exp_f32_e32 v99, v99
	s_nop 0
	v_pk_add_f32 v[98:99], v[98:99], 1.0 op_sel_hi:[1,0]
	s_nop 0
	v_rcp_f32_e32 v98, v98
	v_rcp_f32_e32 v99, v99
	s_nop 0
	v_pk_mul_f32 v[98:99], v[116:117], v[98:99] op_sel_hi:[0,1]
	v_pk_mul_f32 v[104:105], v[104:105], v[98:99]
	v_cvt_pk_bf16_f32 v98, v106, v107
	v_cvt_pk_bf16_f32 v99, v108, v109
	v_cvt_pk_bf16_f32 v100, v102, v103
	v_cvt_pk_bf16_f32 v101, v104, v105
	s_mul_i32 s20, s17, 0x10
	s_mov_b32 s21, 0
	v_lshl_add_u64 v[102:103], s[20:21], 0, v[150:151]
	global_store_dwordx4 v[102:103], v[98:101], off sc1 nt
	s_nop 1
	s_cbranch_vccnz .LBB0_501
	ds_read_b32 v100, v143 offset:128
	s_mov_b64 s[68:69], 0

.LBB0_503:
	s_waitcnt lgkmcnt(0)
	v_mul_f32_e32 v102, 0xbfb8aa3b, v100
	v_pk_mul_f32 v[104:105], v[94:95], v[102:103] op_sel_hi:[1,0]
	v_mul_f32_e32 v100, v100, v100
	v_exp_f32_e32 v104, v104
	v_exp_f32_e32 v105, v105
	v_pk_mul_f32 v[90:91], v[94:95], v[90:91]
	v_pk_mul_f32 v[92:93], v[96:97], v[92:93]
	v_pk_mul_f32 v[88:89], v[84:85], v[88:89]
	v_pk_add_f32 v[104:105], v[104:105], 1.0 op_sel_hi:[1,0]
	s_mov_b64 s[68:69], -1
	v_rcp_f32_e32 v104, v104
	v_rcp_f32_e32 v105, v105
	s_and_b64 vcc, exec, s[52:53]
	v_pk_mul_f32 v[94:95], v[100:101], v[104:105] op_sel_hi:[0,1]
	v_pk_mul_f32 v[90:91], v[90:91], v[94:95]
	v_pk_mul_f32 v[94:95], v[96:97], v[102:103] op_sel_hi:[1,0]
	s_nop 0
	v_exp_f32_e32 v94, v94
	v_exp_f32_e32 v95, v95
	s_nop 0
	v_pk_add_f32 v[94:95], v[94:95], 1.0 op_sel_hi:[1,0]
	s_nop 0
	v_rcp_f32_e32 v94, v94
	v_rcp_f32_e32 v95, v95
	s_nop 0
	v_pk_mul_f32 v[94:95], v[100:101], v[94:95] op_sel_hi:[0,1]
	v_pk_mul_f32 v[92:93], v[92:93], v[94:95]
	v_pk_mul_f32 v[94:95], v[82:83], v[102:103] op_sel_hi:[1,0]
	v_pk_mul_f32 v[82:83], v[82:83], v[86:87]
	v_exp_f32_e32 v94, v94
	v_exp_f32_e32 v95, v95
	s_nop 0
	v_pk_add_f32 v[94:95], v[94:95], 1.0 op_sel_hi:[1,0]
	s_nop 0
	v_rcp_f32_e32 v94, v94
	v_rcp_f32_e32 v95, v95
	s_nop 0
	v_pk_mul_f32 v[86:87], v[100:101], v[94:95] op_sel_hi:[0,1]
	v_pk_mul_f32 v[86:87], v[82:83], v[86:87]
	v_pk_mul_f32 v[82:83], v[84:85], v[102:103] op_sel_hi:[1,0]
	s_nop 0
	v_exp_f32_e32 v82, v82
	v_exp_f32_e32 v83, v83
	s_nop 0
	v_pk_add_f32 v[82:83], v[82:83], 1.0 op_sel_hi:[1,0]
	s_nop 0
	v_rcp_f32_e32 v82, v82
	v_rcp_f32_e32 v83, v83
	s_nop 0
	v_pk_mul_f32 v[82:83], v[100:101], v[82:83] op_sel_hi:[0,1]
	v_pk_mul_f32 v[88:89], v[88:89], v[82:83]
	v_cvt_pk_bf16_f32 v82, v90, v91
	v_cvt_pk_bf16_f32 v83, v92, v93
	v_cvt_pk_bf16_f32 v84, v86, v87
	v_cvt_pk_bf16_f32 v85, v88, v89
	s_mul_i32 s20, s17, 0x20
	s_mov_b32 s21, 0
	v_lshl_add_u64 v[86:87], s[20:21], 0, v[150:151]
	global_store_dwordx4 v[86:87], v[82:85], off sc1 nt
	s_nop 1
	s_cbranch_vccnz .LBB0_505
	ds_read_b32 v84, v143 offset:192
	s_mov_b64 s[68:69], 0

.LBB0_507:
	s_waitcnt lgkmcnt(0)
	v_mul_f32_e32 v86, 0xbfb8aa3b, v84
	v_pk_mul_f32 v[88:89], v[78:79], v[86:87] op_sel_hi:[1,0]
	v_mul_f32_e32 v84, v84, v84
	v_exp_f32_e32 v88, v88
	v_exp_f32_e32 v89, v89
	v_pk_mul_f32 v[74:75], v[78:79], v[74:75]
	v_pk_mul_f32 v[76:77], v[80:81], v[76:77]
	v_pk_mul_f32 v[72:73], v[68:69], v[72:73]
	v_pk_add_f32 v[88:89], v[88:89], 1.0 op_sel_hi:[1,0]
	s_mov_b64 s[68:69], -1
	v_rcp_f32_e32 v88, v88
	v_rcp_f32_e32 v89, v89
	s_and_b64 vcc, exec, s[52:53]
	v_pk_mul_f32 v[78:79], v[84:85], v[88:89] op_sel_hi:[0,1]
	v_pk_mul_f32 v[74:75], v[74:75], v[78:79]
	v_pk_mul_f32 v[78:79], v[80:81], v[86:87] op_sel_hi:[1,0]
	s_nop 0
	v_exp_f32_e32 v78, v78
	v_exp_f32_e32 v79, v79
	s_nop 0
	v_pk_add_f32 v[78:79], v[78:79], 1.0 op_sel_hi:[1,0]
	s_nop 0
	v_rcp_f32_e32 v78, v78
	v_rcp_f32_e32 v79, v79
	s_nop 0
	v_pk_mul_f32 v[78:79], v[84:85], v[78:79] op_sel_hi:[0,1]
	v_pk_mul_f32 v[76:77], v[76:77], v[78:79]
	v_pk_mul_f32 v[78:79], v[66:67], v[86:87] op_sel_hi:[1,0]
	v_pk_mul_f32 v[66:67], v[66:67], v[70:71]
	v_exp_f32_e32 v78, v78
	v_exp_f32_e32 v79, v79
	s_nop 0
	v_pk_add_f32 v[78:79], v[78:79], 1.0 op_sel_hi:[1,0]
	s_nop 0
	v_rcp_f32_e32 v78, v78
	v_rcp_f32_e32 v79, v79
	s_nop 0
	v_pk_mul_f32 v[70:71], v[84:85], v[78:79] op_sel_hi:[0,1]
	v_pk_mul_f32 v[70:71], v[66:67], v[70:71]
	v_pk_mul_f32 v[66:67], v[68:69], v[86:87] op_sel_hi:[1,0]
	s_nop 0
	v_exp_f32_e32 v66, v66
	v_exp_f32_e32 v67, v67
	s_nop 0
	v_pk_add_f32 v[66:67], v[66:67], 1.0 op_sel_hi:[1,0]
	s_nop 0
	v_rcp_f32_e32 v66, v66
	v_rcp_f32_e32 v67, v67
	s_nop 0
	v_pk_mul_f32 v[66:67], v[84:85], v[66:67] op_sel_hi:[0,1]
	v_pk_mul_f32 v[72:73], v[72:73], v[66:67]
	v_cvt_pk_bf16_f32 v66, v74, v75
	v_cvt_pk_bf16_f32 v67, v76, v77
	v_cvt_pk_bf16_f32 v68, v70, v71
	v_cvt_pk_bf16_f32 v69, v72, v73
	s_mul_i32 s20, s17, 0x30
	s_mov_b32 s21, 0
	v_lshl_add_u64 v[70:71], s[20:21], 0, v[150:151]
	global_store_dwordx4 v[70:71], v[66:69], off sc1 nt
	s_nop 1
	s_cbranch_vccnz .LBB0_509
	ds_read_b32 v68, v143 offset:512
	s_mov_b64 s[68:69], 0

.LBB0_511:
	s_waitcnt lgkmcnt(0)
	v_mul_f32_e32 v70, 0xbfb8aa3b, v68
	v_pk_mul_f32 v[72:73], v[62:63], v[70:71] op_sel_hi:[1,0]
	v_mul_f32_e32 v68, v68, v68
	v_exp_f32_e32 v72, v72
	v_exp_f32_e32 v73, v73
	v_pk_mul_f32 v[58:59], v[62:63], v[58:59]
	v_pk_mul_f32 v[60:61], v[64:65], v[60:61]
	v_pk_mul_f32 v[56:57], v[52:53], v[56:57]
	v_pk_add_f32 v[72:73], v[72:73], 1.0 op_sel_hi:[1,0]
	s_mov_b64 s[68:69], -1
	v_rcp_f32_e32 v72, v72
	v_rcp_f32_e32 v73, v73
	s_and_b64 vcc, exec, s[52:53]
	v_pk_mul_f32 v[62:63], v[68:69], v[72:73] op_sel_hi:[0,1]
	v_pk_mul_f32 v[58:59], v[58:59], v[62:63]
	v_pk_mul_f32 v[62:63], v[64:65], v[70:71] op_sel_hi:[1,0]
	s_nop 0
	v_exp_f32_e32 v62, v62
	v_exp_f32_e32 v63, v63
	s_nop 0
	v_pk_add_f32 v[62:63], v[62:63], 1.0 op_sel_hi:[1,0]
	s_nop 0
	v_rcp_f32_e32 v62, v62
	v_rcp_f32_e32 v63, v63
	s_nop 0
	v_pk_mul_f32 v[62:63], v[68:69], v[62:63] op_sel_hi:[0,1]
	v_pk_mul_f32 v[60:61], v[60:61], v[62:63]
	v_pk_mul_f32 v[62:63], v[50:51], v[70:71] op_sel_hi:[1,0]
	v_pk_mul_f32 v[50:51], v[50:51], v[54:55]
	v_exp_f32_e32 v62, v62
	v_exp_f32_e32 v63, v63
	s_nop 0
	v_pk_add_f32 v[62:63], v[62:63], 1.0 op_sel_hi:[1,0]
	s_nop 0
	v_rcp_f32_e32 v62, v62
	v_rcp_f32_e32 v63, v63
	s_nop 0
	v_pk_mul_f32 v[54:55], v[68:69], v[62:63] op_sel_hi:[0,1]
	v_pk_mul_f32 v[54:55], v[50:51], v[54:55]
	v_pk_mul_f32 v[50:51], v[52:53], v[70:71] op_sel_hi:[1,0]
	s_nop 0
	v_exp_f32_e32 v50, v50
	v_exp_f32_e32 v51, v51
	s_nop 0
	v_pk_add_f32 v[50:51], v[50:51], 1.0 op_sel_hi:[1,0]
	s_nop 0
	v_rcp_f32_e32 v50, v50
	v_rcp_f32_e32 v51, v51
	s_nop 0
	v_pk_mul_f32 v[50:51], v[68:69], v[50:51] op_sel_hi:[0,1]
	v_pk_mul_f32 v[56:57], v[56:57], v[50:51]
	v_cvt_pk_bf16_f32 v50, v58, v59
	v_cvt_pk_bf16_f32 v51, v60, v61
	v_cvt_pk_bf16_f32 v52, v54, v55
	v_cvt_pk_bf16_f32 v53, v56, v57
	s_mul_i32 s20, s17, 0x80
	s_mov_b32 s21, 0
	v_lshl_add_u64 v[54:55], s[20:21], 0, v[150:151]
	global_store_dwordx4 v[54:55], v[50:53], off sc1 nt
	s_nop 1
	s_cbranch_vccnz .LBB0_513
	ds_read_b32 v52, v143 offset:576
	s_mov_b64 s[68:69], 0

.LBB0_515:
	s_waitcnt lgkmcnt(0)
	v_mul_f32_e32 v54, 0xbfb8aa3b, v52
	v_pk_mul_f32 v[56:57], v[46:47], v[54:55] op_sel_hi:[1,0]
	v_mul_f32_e32 v52, v52, v52
	v_exp_f32_e32 v56, v56
	v_exp_f32_e32 v57, v57
	v_pk_mul_f32 v[42:43], v[46:47], v[42:43]
	v_pk_mul_f32 v[44:45], v[48:49], v[44:45]
	v_pk_mul_f32 v[40:41], v[36:37], v[40:41]
	v_pk_add_f32 v[56:57], v[56:57], 1.0 op_sel_hi:[1,0]
	s_mov_b64 s[68:69], -1
	v_rcp_f32_e32 v56, v56
	v_rcp_f32_e32 v57, v57
	s_and_b64 vcc, exec, s[52:53]
	v_pk_mul_f32 v[46:47], v[52:53], v[56:57] op_sel_hi:[0,1]
	v_pk_mul_f32 v[42:43], v[42:43], v[46:47]
	v_pk_mul_f32 v[46:47], v[48:49], v[54:55] op_sel_hi:[1,0]
	s_nop 0
	v_exp_f32_e32 v46, v46
	v_exp_f32_e32 v47, v47
	s_nop 0
	v_pk_add_f32 v[46:47], v[46:47], 1.0 op_sel_hi:[1,0]
	s_nop 0
	v_rcp_f32_e32 v46, v46
	v_rcp_f32_e32 v47, v47
	s_nop 0
	v_pk_mul_f32 v[46:47], v[52:53], v[46:47] op_sel_hi:[0,1]
	v_pk_mul_f32 v[44:45], v[44:45], v[46:47]
	v_pk_mul_f32 v[46:47], v[34:35], v[54:55] op_sel_hi:[1,0]
	v_pk_mul_f32 v[34:35], v[34:35], v[38:39]
	v_exp_f32_e32 v46, v46
	v_exp_f32_e32 v47, v47
	s_nop 0
	v_pk_add_f32 v[46:47], v[46:47], 1.0 op_sel_hi:[1,0]
	s_nop 0
	v_rcp_f32_e32 v46, v46
	v_rcp_f32_e32 v47, v47
	s_nop 0
	v_pk_mul_f32 v[38:39], v[52:53], v[46:47] op_sel_hi:[0,1]
	v_pk_mul_f32 v[38:39], v[34:35], v[38:39]
	v_pk_mul_f32 v[34:35], v[36:37], v[54:55] op_sel_hi:[1,0]
	s_nop 0
	v_exp_f32_e32 v34, v34
	v_exp_f32_e32 v35, v35
	s_nop 0
	v_pk_add_f32 v[34:35], v[34:35], 1.0 op_sel_hi:[1,0]
	s_nop 0
	v_rcp_f32_e32 v34, v34
	v_rcp_f32_e32 v35, v35
	s_nop 0
	v_pk_mul_f32 v[34:35], v[52:53], v[34:35] op_sel_hi:[0,1]
	v_pk_mul_f32 v[40:41], v[40:41], v[34:35]
	v_cvt_pk_bf16_f32 v34, v42, v43
	v_cvt_pk_bf16_f32 v35, v44, v45
	v_cvt_pk_bf16_f32 v36, v38, v39
	v_cvt_pk_bf16_f32 v37, v40, v41
	s_mul_i32 s20, s17, 0x90
	s_mov_b32 s21, 0
	v_lshl_add_u64 v[38:39], s[20:21], 0, v[150:151]
	global_store_dwordx4 v[38:39], v[34:37], off sc1 nt
	s_nop 1
	s_cbranch_vccnz .LBB0_517
	ds_read_b32 v36, v143 offset:640
	s_mov_b64 s[68:69], 0

.LBB0_519:
	s_waitcnt lgkmcnt(0)
	v_mul_f32_e32 v38, 0xbfb8aa3b, v36
	v_pk_mul_f32 v[40:41], v[30:31], v[38:39] op_sel_hi:[1,0]
	v_mul_f32_e32 v36, v36, v36
	v_exp_f32_e32 v40, v40
	v_exp_f32_e32 v41, v41
	v_pk_mul_f32 v[26:27], v[30:31], v[26:27]
	v_pk_mul_f32 v[28:29], v[32:33], v[28:29]
	v_pk_mul_f32 v[24:25], v[20:21], v[24:25]
	v_pk_add_f32 v[40:41], v[40:41], 1.0 op_sel_hi:[1,0]
	s_mov_b64 s[68:69], -1
	v_rcp_f32_e32 v40, v40
	v_rcp_f32_e32 v41, v41
	s_and_b64 vcc, exec, s[52:53]
	v_pk_mul_f32 v[30:31], v[36:37], v[40:41] op_sel_hi:[0,1]
	v_pk_mul_f32 v[26:27], v[26:27], v[30:31]
	v_pk_mul_f32 v[30:31], v[32:33], v[38:39] op_sel_hi:[1,0]
	s_nop 0
	v_exp_f32_e32 v30, v30
	v_exp_f32_e32 v31, v31
	s_nop 0
	v_pk_add_f32 v[30:31], v[30:31], 1.0 op_sel_hi:[1,0]
	s_nop 0
	v_rcp_f32_e32 v30, v30
	v_rcp_f32_e32 v31, v31
	s_nop 0
	v_pk_mul_f32 v[30:31], v[36:37], v[30:31] op_sel_hi:[0,1]
	v_pk_mul_f32 v[28:29], v[28:29], v[30:31]
	v_pk_mul_f32 v[30:31], v[18:19], v[38:39] op_sel_hi:[1,0]
	v_pk_mul_f32 v[18:19], v[18:19], v[22:23]
	v_exp_f32_e32 v30, v30
	v_exp_f32_e32 v31, v31
	s_nop 0
	v_pk_add_f32 v[30:31], v[30:31], 1.0 op_sel_hi:[1,0]
	s_nop 0
	v_rcp_f32_e32 v30, v30
	v_rcp_f32_e32 v31, v31
	s_nop 0
	v_pk_mul_f32 v[22:23], v[36:37], v[30:31] op_sel_hi:[0,1]
	v_pk_mul_f32 v[22:23], v[18:19], v[22:23]
	v_pk_mul_f32 v[18:19], v[20:21], v[38:39] op_sel_hi:[1,0]
	s_nop 0
	v_exp_f32_e32 v18, v18
	v_exp_f32_e32 v19, v19
	s_nop 0
	v_pk_add_f32 v[18:19], v[18:19], 1.0 op_sel_hi:[1,0]
	s_nop 0
	v_rcp_f32_e32 v18, v18
	v_rcp_f32_e32 v19, v19
	s_nop 0
	v_pk_mul_f32 v[18:19], v[36:37], v[18:19] op_sel_hi:[0,1]
	v_pk_mul_f32 v[24:25], v[24:25], v[18:19]
	v_cvt_pk_bf16_f32 v18, v26, v27
	v_cvt_pk_bf16_f32 v19, v28, v29
	v_cvt_pk_bf16_f32 v20, v22, v23
	v_cvt_pk_bf16_f32 v21, v24, v25
	s_mul_i32 s20, s17, 0xa0
	s_mov_b32 s21, 0
	v_lshl_add_u64 v[22:23], s[20:21], 0, v[150:151]
	global_store_dwordx4 v[22:23], v[18:21], off sc1 nt
	s_nop 1
	s_cbranch_vccnz .LBB0_521
	ds_read_b32 v20, v143 offset:704
	s_mov_b64 s[68:69], 0

.LBB0_523:
	s_waitcnt lgkmcnt(0)
	v_mul_f32_e32 v22, 0xbfb8aa3b, v20
	v_pk_mul_f32 v[24:25], v[14:15], v[22:23] op_sel_hi:[1,0]
	v_mul_f32_e32 v20, v20, v20
	v_exp_f32_e32 v24, v24
	v_exp_f32_e32 v25, v25
	v_pk_mul_f32 v[10:11], v[14:15], v[10:11]
	v_pk_mul_f32 v[12:13], v[16:17], v[12:13]
	v_pk_mul_f32 v[2:3], v[6:7], v[2:3]
	v_pk_add_f32 v[24:25], v[24:25], 1.0 op_sel_hi:[1,0]
	v_pk_mul_f32 v[4:5], v[8:9], v[4:5]
	v_rcp_f32_e32 v24, v24
	v_rcp_f32_e32 v25, v25
	s_mov_b64 s[68:69], -1
	s_andn2_b64 vcc, exec, s[54:55]
	v_pk_mul_f32 v[14:15], v[20:21], v[24:25] op_sel_hi:[0,1]
	v_pk_mul_f32 v[10:11], v[10:11], v[14:15]
	v_pk_mul_f32 v[14:15], v[16:17], v[22:23] op_sel_hi:[1,0]
	s_nop 0
	v_exp_f32_e32 v14, v14
	v_exp_f32_e32 v15, v15
	s_nop 0
	v_pk_add_f32 v[14:15], v[14:15], 1.0 op_sel_hi:[1,0]
	s_nop 0
	v_rcp_f32_e32 v14, v14
	v_rcp_f32_e32 v15, v15
	s_nop 0
	v_pk_mul_f32 v[14:15], v[20:21], v[14:15] op_sel_hi:[0,1]
	v_pk_mul_f32 v[12:13], v[12:13], v[14:15]
	v_pk_mul_f32 v[14:15], v[6:7], v[22:23] op_sel_hi:[1,0]
	s_nop 0
	v_exp_f32_e32 v14, v14
	v_exp_f32_e32 v15, v15
	s_nop 0
	v_pk_add_f32 v[14:15], v[14:15], 1.0 op_sel_hi:[1,0]
	s_nop 0
	v_rcp_f32_e32 v14, v14
	v_rcp_f32_e32 v15, v15
	s_nop 0
	v_pk_mul_f32 v[6:7], v[20:21], v[14:15] op_sel_hi:[0,1]
	v_pk_mul_f32 v[6:7], v[2:3], v[6:7]
	v_pk_mul_f32 v[2:3], v[8:9], v[22:23] op_sel_hi:[1,0]
	s_nop 0
	v_exp_f32_e32 v2, v2
	v_exp_f32_e32 v3, v3
	s_nop 0
	v_pk_add_f32 v[2:3], v[2:3], 1.0 op_sel_hi:[1,0]
	s_nop 0
	v_rcp_f32_e32 v2, v2
	v_rcp_f32_e32 v3, v3
	s_nop 0
	v_pk_mul_f32 v[2:3], v[20:21], v[2:3] op_sel_hi:[0,1]
	v_pk_mul_f32 v[8:9], v[4:5], v[2:3]
	v_cvt_pk_bf16_f32 v2, v10, v11
	v_cvt_pk_bf16_f32 v3, v12, v13
	v_cvt_pk_bf16_f32 v4, v6, v7
	v_cvt_pk_bf16_f32 v5, v8, v9
	s_mul_i32 s20, s17, 0xb0
	s_mov_b32 s21, 0
	v_lshl_add_u64 v[6:7], s[20:21], 0, v[150:151]
	global_store_dwordx4 v[6:7], v[2:5], off sc1 nt
	s_cbranch_vccnz .LBB0_484
	s_andn2_b64 vcc, exec, s[6:7]
	s_cbranch_vccnz .LBB0_483
	s_barrier
	s_branch .LBB0_483
